# early L2 write-back: first workgroup of each XCD to arrive at a grid barrier issues buffer_wbl2 (K=0), on top of ao1
# baseline (speedup 1.0000x reference)
.LBB0_132:
	s_or_b64 exec, exec, s[12:13]
	v_cvt_f32_u32_e32 v4, v2
	s_waitcnt vmcnt(0)
	v_readfirstlane_b32 s2, v3
	v_sub_u32_e32 v3, 0, v2
	v_rcp_iflag_f32_e32 v4, v4
	v_add_u32_e32 v5, s2, v1
	v_mul_f32_e32 v4, 0x4f7ffffe, v4
	v_cvt_u32_f32_e32 v4, v4
	v_mul_lo_u32 v1, v3, v4
	v_mul_hi_u32 v1, v4, v1
	v_add_u32_e32 v1, v4, v1
	v_mul_hi_u32 v1, v5, v1
	v_mul_lo_u32 v3, v1, v2
	v_sub_u32_e32 v3, v5, v3
	v_add_u32_e32 v4, 1, v1
	v_cmp_ge_u32_e32 vcc, v3, v2
	s_nop 1
	v_cndmask_b32_e32 v1, v1, v4, vcc
	v_sub_u32_e32 v4, v3, v2
	v_cndmask_b32_e32 v3, v3, v4, vcc
	v_add_u32_e32 v4, 1, v1
	v_cmp_ge_u32_e32 vcc, v3, v2
	v_add_u32_e32 v3, 1, v5
	s_nop 0
	v_cndmask_b32_e32 v1, v1, v4, vcc
	v_mul_lo_u32 v4, v2, v1
	v_add_u32_e32 v2, v4, v2
	v_cmp_ne_u32_e32 vcc, v3, v2
	s_and_saveexec_b64 s[2:3], vcc
	s_xor_b64 s[10:11], exec, s[2:3]
	s_cbranch_execz .LBB0_146
	s_waitcnt lgkmcnt(0)
	v_and_b32_e32 v0, 31, v5
	v_cmp_eq_u32_e32 vcc, 0, v0
	s_cbranch_vccz .Lef_skip_0
	buffer_wbl2 sc1
.Lef_skip_0:
	v_mov_b32_e32 v0, 0x2000
	buffer_inv sc1
	global_load_dword v0, v0, s[8:9] offset:1024 sc1
	s_add_u32 s16, s8, 0x2400
	s_addc_u32 s17, s9, 0
	s_waitcnt vmcnt(0)
	v_cmp_eq_u32_e32 vcc, v0, v1
	s_and_saveexec_b64 s[12:13], vcc
	s_cbranch_execz .LBB0_145
	s_add_u32 s14, s6, 0x10200
	s_addc_u32 s15, s7, 0
	s_mov_b32 s2, 1
	s_mov_b64 s[18:19], 0
	v_mov_b32_e32 v0, 0
	s_branch .LBB0_136

.LBB0_209:
	s_or_b64 exec, exec, s[12:13]
	v_cvt_f32_u32_e32 v5, v3
	s_waitcnt vmcnt(0)
	v_readfirstlane_b32 s10, v4
	v_sub_u32_e32 v4, 0, v3
	v_rcp_iflag_f32_e32 v5, v5
	v_add_u32_e32 v6, s10, v1
	v_mul_f32_e32 v5, 0x4f7ffffe, v5
	v_cvt_u32_f32_e32 v5, v5
	v_mul_lo_u32 v1, v4, v5
	v_mul_hi_u32 v1, v5, v1
	v_add_u32_e32 v1, v5, v1
	v_mul_hi_u32 v1, v6, v1
	v_mul_lo_u32 v4, v1, v3
	v_sub_u32_e32 v4, v6, v4
	v_add_u32_e32 v5, 1, v1
	v_cmp_ge_u32_e32 vcc, v4, v3
	s_nop 1
	v_cndmask_b32_e32 v1, v1, v5, vcc
	v_sub_u32_e32 v5, v4, v3
	v_cndmask_b32_e32 v4, v4, v5, vcc
	v_add_u32_e32 v5, 1, v1
	v_cmp_ge_u32_e32 vcc, v4, v3
	v_add_u32_e32 v4, 1, v6
	s_nop 0
	v_cndmask_b32_e32 v1, v1, v5, vcc
	v_mul_lo_u32 v5, v3, v1
	v_add_u32_e32 v3, v5, v3
	v_cmp_ne_u32_e32 vcc, v4, v3
	s_and_saveexec_b64 s[10:11], vcc
	s_xor_b64 s[10:11], exec, s[10:11]
	s_cbranch_execz .LBB0_223
	s_waitcnt lgkmcnt(0)
	v_and_b32_e32 v2, 31, v6
	v_cmp_eq_u32_e32 vcc, 0, v2
	s_cbranch_vccz .Lef_skip_1
	buffer_wbl2 sc1
.Lef_skip_1:
	v_mov_b32_e32 v2, 0x2000
	buffer_inv sc1
	global_load_dword v2, v2, s[8:9] offset:1024 sc1
	s_add_u32 s16, s8, 0x2400
	s_addc_u32 s17, s9, 0
	s_waitcnt vmcnt(0)
	v_cmp_eq_u32_e32 vcc, v2, v1
	s_and_saveexec_b64 s[12:13], vcc
	s_cbranch_execz .LBB0_222
	s_add_u32 s14, s6, 0x10200
	s_addc_u32 s15, s7, 0
	s_mov_b32 s18, 1
	s_mov_b64 s[20:21], 0
	s_branch .LBB0_213

.LBB0_1286:
	s_or_b64 exec, exec, s[12:13]
	v_cvt_f32_u32_e32 v5, v3
	s_waitcnt vmcnt(0)
	v_readfirstlane_b32 s10, v4
	v_sub_u32_e32 v4, 0, v3
	v_rcp_iflag_f32_e32 v5, v5
	v_add_u32_e32 v6, s10, v1
	v_mul_f32_e32 v5, 0x4f7ffffe, v5
	v_cvt_u32_f32_e32 v5, v5
	v_mul_lo_u32 v1, v4, v5
	v_mul_hi_u32 v1, v5, v1
	v_add_u32_e32 v1, v5, v1
	v_mul_hi_u32 v1, v6, v1
	v_mul_lo_u32 v4, v1, v3
	v_sub_u32_e32 v4, v6, v4
	v_add_u32_e32 v5, 1, v1
	v_cmp_ge_u32_e32 vcc, v4, v3
	s_nop 1
	v_cndmask_b32_e32 v1, v1, v5, vcc
	v_sub_u32_e32 v5, v4, v3
	v_cndmask_b32_e32 v4, v4, v5, vcc
	v_add_u32_e32 v5, 1, v1
	v_cmp_ge_u32_e32 vcc, v4, v3
	v_add_u32_e32 v4, 1, v6
	s_nop 0
	v_cndmask_b32_e32 v1, v1, v5, vcc
	v_mul_lo_u32 v5, v3, v1
	v_add_u32_e32 v3, v5, v3
	v_cmp_ne_u32_e32 vcc, v4, v3
	s_and_saveexec_b64 s[10:11], vcc
	s_xor_b64 s[10:11], exec, s[10:11]
	s_mov_b32 s54, 0x8000
	s_cbranch_execz .LBB0_1300
	s_waitcnt lgkmcnt(0)
	v_and_b32_e32 v2, 31, v6
	v_cmp_eq_u32_e32 vcc, 0, v2
	s_cbranch_vccz .Lef_skip_8
	buffer_wbl2 sc1
.Lef_skip_8:
	v_mov_b32_e32 v2, 0x2000
	buffer_inv sc1
	global_load_dword v2, v2, s[8:9] offset:1024 sc1
	s_add_u32 s16, s8, 0x2400
	s_addc_u32 s17, s9, 0
	s_waitcnt vmcnt(0)
	v_cmp_eq_u32_e32 vcc, v2, v1
	s_and_saveexec_b64 s[12:13], vcc
	s_cbranch_execz .LBB0_1299
	s_add_u32 s14, s6, 0x10200
	s_addc_u32 s15, s7, 0
	s_mov_b32 s38, 1
	s_mov_b64 s[18:19], 0
	s_branch .LBB0_1290
